# v033 + removed the L2 invalidate (buffer_inv sc1) in the P6 split-K consumer: the partials are read with sc1 loads only
# speedup vs baseline: 1.0101x; 1.0101x over previous
; __global__ void __launch_bounds__(512, 2) hybrid_fwd(Params p) {
;     ...
;         if (PH(8)) { PHB
;             if (tid == 0) { unsigned* cw_ = (unsigned*)ws + 3840 + 32 * l + (c & 31); unsigned sp_ = 0;
;                 while (__hip_atomic_load(cw_, __ATOMIC_RELAXED, __HIP_MEMORY_SCOPE_AGENT) < 4u) { __builtin_amdgcn_s_sleep(2); if (++sp_ > (1u << 22)) break; }
;                 __builtin_amdgcn_fence(__ATOMIC_ACQUIRE, "agent"); asm volatile("s_waitcnt vmcnt(0)" ::: "memory"); }
;             __syncthreads();
.Lp6_spin_done:
	s_nop 0
	s_waitcnt vmcnt(0)
